# v35: v34 + HGRN prompt-item loop (.LBB0_594) decay scans fused into v_mul_f32_dpp (40 x 3 ops -> 40)
# speedup vs baseline: 1.0090x; 1.0090x over previous
.LBB0_594:
	v_mul_f32_e64 v42, |v30|, s80
	v_exp_f32_e32 v42, v42
	v_mul_f32_e64 v43, |v31|, s80
	v_exp_f32_e32 v43, v43
	s_cmpk_lg_i32 s17, 0x1c0
	s_cselect_b32 s60, s42, 0x70
	v_add_f32_e32 v46, 1.0, v42
	s_waitcnt vmcnt(0)
	v_mov_b64_e32 v[28:29], v[20:21]
	s_lshl_b64 s[0:1], s[60:61], 1
	v_rcp_f32_e32 v48, v46
	v_add_f32_e32 v46, 1.0, v43
	v_mov_b64_e32 v[26:27], v[18:19]
	v_lshl_add_u64 v[18:19], v[38:39], 0, s[0:1]
	v_lshl_add_u64 v[22:23], v[40:41], 0, s[0:1]
	v_add_u32_e32 v34, s17, v51
	v_rcp_f32_e32 v49, v46
	global_load_dwordx4 v[18:21], v[18:19], off offset:3072
	v_cmp_nle_f32_e64 s[0:1], 0, v30
	global_load_dwordx4 v[22:25], v[22:23], off
	ds_read_b128 v[80:83], v34
	ds_read_b128 v[34:37], v34 offset:16
	v_pk_mul_f32 v[42:43], v[42:43], v[48:49]
	v_cmp_nle_f32_e32 vcc, 0, v31
	v_cndmask_b32_e64 v79, v48, v42, s[0:1]
	s_waitcnt lgkmcnt(1)
	v_pk_add_f32 v[30:31], v[80:81], 1.0 op_sel_hi:[1,0] neg_lo:[1,0] neg_hi:[1,0]
	v_cndmask_b32_e64 v42, v42, v48, s[0:1]
	v_fma_f32 v79, v30, v79, v80
	v_cndmask_b32_e32 v80, v49, v43, vcc
	v_cndmask_b32_e32 v43, v43, v49, vcc
	v_fma_f32 v48, v31, v80, v81
	v_pk_mul_f32 v[42:43], v[30:31], v[42:43]
	v_mul_f32_e64 v44, |v32|, s80
	v_mov_b32_e32 v30, v79
	s_nop 1
	v_mul_f32_dpp v30, v30, v30 row_shr:1 row_mask:0xf bank_mask:0xf
	v_mov_b32_e32 v31, v48
	s_nop 1
	v_mul_f32_dpp v31, v31, v31 row_shr:1 row_mask:0xf bank_mask:0xf
	v_exp_f32_e32 v54, v44
	v_mul_f32_e64 v44, |v33|, s80
	v_mul_f32_dpp v30, v30, v30 row_shr:2 row_mask:0xf bank_mask:0xf
	v_exp_f32_e32 v55, v44
	v_add_f32_e32 v46, 1.0, v54
	v_mul_f32_dpp v31, v31, v31 row_shr:2 row_mask:0xf bank_mask:0xf
	v_rcp_f32_e32 v86, v46
	v_add_f32_e32 v46, 1.0, v55
	v_mul_f32_dpp v30, v30, v30 row_shr:4 row_mask:0xf bank_mask:0xf
	v_rcp_f32_e32 v87, v46
	v_cmp_nle_f32_e32 vcc, 0, v33
	v_mul_f32_dpp v31, v31, v31 row_shr:4 row_mask:0xf bank_mask:0xf
	v_pk_mul_f32 v[54:55], v[54:55], v[86:87]
	v_mul_f32_e64 v44, |v75|, s80
	v_mul_f32_dpp v30, v30, v30 row_shr:8 row_mask:0xf bank_mask:0xf
	v_exp_f32_e32 v84, v44
	v_mul_f32_e64 v44, |v77|, s80
	v_mul_f32_dpp v31, v31, v31 row_shr:8 row_mask:0xf bank_mask:0xf
	v_exp_f32_e32 v85, v44
	v_add_f32_e32 v46, 1.0, v84
	v_mul_f32_dpp v30, v30, v30 row_bcast:15 row_mask:0xa bank_mask:0xf
	v_rcp_f32_e32 v88, v46
	v_add_f32_e32 v46, 1.0, v85
	v_mul_f32_dpp v31, v31, v31 row_bcast:15 row_mask:0xa bank_mask:0xf
	v_max_f32_e32 v48, 0x554ad2e, v30
	v_max_f32_e32 v49, 0x554ad2e, v31
	v_rcp_f32_e32 v80, v48
	v_rcp_f32_e32 v81, v49
	v_readlane_b32 s0, v48, 31
	v_readlane_b32 s1, v48, 63
	v_rcp_f32_e32 v89, v46
	v_pk_mul_f32 v[42:43], v[42:43], v[80:81]
	v_lshlrev_b32_e32 v80, 16, v26
	v_and_b32_e32 v81, 0xffff0000, v26
	v_mul_f32_e32 v26, 0xbfb8aa3b, v80
	v_exp_f32_e32 v26, v26
	v_mul_f32_e32 v90, 0xbfb8aa3b, v81
	v_exp_f32_e32 v91, v90
	v_mov_b32_e32 v30, s1
	v_add_f32_e32 v26, 1.0, v26
	v_rcp_f32_e32 v90, v26
	v_add_f32_e32 v26, 1.0, v91
	v_rcp_f32_e32 v91, v26
	v_mov_b32_e32 v31, s0
	v_readlane_b32 s0, v49, 31
	v_readlane_b32 s1, v49, 63
	v_cndmask_b32_e64 v30, v30, v31, s[2:3]
	v_mov_b32_e32 v79, s0
	v_mov_b32_e32 v31, s1
	v_pk_mul_f32 v[80:81], v[90:91], v[80:81]
	v_cmp_nle_f32_e64 s[0:1], 0, v32
	v_pk_mul_f32 v[48:49], v[80:81], v[48:49]
	v_pk_add_f32 v[32:33], v[82:83], 1.0 op_sel_hi:[1,0] neg_lo:[1,0] neg_hi:[1,0]
	v_cndmask_b32_e64 v26, v86, v54, s[0:1]
	v_cndmask_b32_e32 v80, v87, v55, vcc
	v_cndmask_b32_e32 v55, v55, v87, vcc
	v_cndmask_b32_e64 v54, v54, v86, s[0:1]
	v_fma_f32 v26, v32, v26, v82
	v_pk_mul_f32 v[54:55], v[32:33], v[54:55]
	v_fmac_f32_e32 v83, v33, v80
	v_mul_f32_dpp v26, v26, v26 row_shr:1 row_mask:0xf bank_mask:0xf
	v_cmp_nle_f32_e32 vcc, 0, v77
	v_mov_b32_e32 v32, v83
	s_nop 1
	v_mul_f32_dpp v32, v32, v32 row_shr:1 row_mask:0xf bank_mask:0xf
	v_mul_f32_dpp v26, v26, v26 row_shr:2 row_mask:0xf bank_mask:0xf
	v_mul_f32_e64 v44, |v71|, s80
	v_mul_f32_e64 v45, |v73|, s80
	v_mul_f32_dpp v32, v32, v32 row_shr:2 row_mask:0xf bank_mask:0xf
	v_exp_f32_e32 v44, v44
	v_exp_f32_e32 v45, v45
	v_mul_f32_dpp v26, v26, v26 row_shr:4 row_mask:0xf bank_mask:0xf
	v_add_f32_e32 v46, 1.0, v44
	v_add_f32_e32 v47, 1.0, v45
	v_mul_f32_dpp v32, v32, v32 row_shr:4 row_mask:0xf bank_mask:0xf
	v_rcp_f32_e32 v46, v46
	v_rcp_f32_e32 v47, v47
	v_mul_f32_dpp v26, v26, v26 row_shr:8 row_mask:0xf bank_mask:0xf
	v_cndmask_b32_e64 v31, v31, v79, s[2:3]
	v_mul_f32_e32 v79, v42, v30
	v_mul_f32_dpp v32, v32, v32 row_shr:8 row_mask:0xf bank_mask:0xf
	v_mul_f32_e32 v90, v43, v31
	v_cvt_pk_bf16_f32 v42, v42, v43
	v_mul_f32_dpp v26, v26, v26 row_bcast:15 row_mask:0xa bank_mask:0xf
	v_max_f32_e32 v80, 0x554ad2e, v26
	v_rcp_f32_e32 v82, v80
	v_mul_f32_dpp v32, v32, v32 row_bcast:15 row_mask:0xa bank_mask:0xf
	v_max_f32_e32 v81, 0x554ad2e, v32
	v_rcp_f32_e32 v83, v81
	v_readlane_b32 s0, v80, 31
	v_readlane_b32 s1, v80, 63
	v_pk_mul_f32 v[54:55], v[54:55], v[82:83]
	s_nop 0
	v_mov_b32_e32 v26, s1
	v_mov_b32_e32 v32, s0
	v_readlane_b32 s0, v81, 31
	v_readlane_b32 s1, v81, 63
	v_cndmask_b32_e64 v32, v26, v32, s[2:3]
	v_mov_b32_e32 v33, s0
	v_mov_b32_e32 v26, s1
	v_cndmask_b32_e64 v33, v26, v33, s[2:3]
	v_lshlrev_b32_e32 v26, 16, v27
	v_and_b32_e32 v27, 0xffff0000, v27
	v_mul_f32_e32 v82, 0xbfb8aa3b, v26
	v_mul_f32_e32 v83, 0xbfb8aa3b, v27
	v_exp_f32_e32 v82, v82
	v_exp_f32_e32 v83, v83
	v_cmp_nle_f32_e64 s[0:1], 0, v75
	v_cvt_pk_bf16_f32 v43, v54, v55
	v_add_f32_e32 v82, 1.0, v82
	v_add_f32_e32 v83, 1.0, v83
	v_rcp_f32_e32 v82, v82
	v_rcp_f32_e32 v83, v83
	v_mul_f32_e32 v91, v54, v32
	v_mul_f32_e32 v92, v55, v33
	v_pk_mul_f32 v[26:27], v[82:83], v[26:27]
	v_pk_mul_f32 v[80:81], v[26:27], v[80:81]
	v_pk_mul_f32 v[26:27], v[84:85], v[88:89]
	s_waitcnt lgkmcnt(0)
	v_pk_add_f32 v[82:83], v[34:35], 1.0 op_sel_hi:[1,0] neg_lo:[1,0] neg_hi:[1,0]
	v_cndmask_b32_e64 v75, v88, v26, s[0:1]
	v_fma_f32 v34, v82, v75, v34
	v_cndmask_b32_e32 v75, v89, v27, vcc
	v_fma_f32 v35, v83, v75, v35
	v_cndmask_b32_e32 v27, v27, v89, vcc
	v_cndmask_b32_e64 v26, v26, v88, s[0:1]
	v_mul_f32_dpp v34, v34, v34 row_shr:1 row_mask:0xf bank_mask:0xf
	v_pk_mul_f32 v[26:27], v[82:83], v[26:27]
	v_cmp_nle_f32_e32 vcc, 0, v73
	v_mul_f32_dpp v35, v35, v35 row_shr:1 row_mask:0xf bank_mask:0xf
	v_mul_f32_dpp v34, v34, v34 row_shr:2 row_mask:0xf bank_mask:0xf
	s_nop 0
	v_mul_f32_dpp v35, v35, v35 row_shr:2 row_mask:0xf bank_mask:0xf
	v_mul_f32_dpp v34, v34, v34 row_shr:4 row_mask:0xf bank_mask:0xf
	s_nop 0
	v_mul_f32_dpp v35, v35, v35 row_shr:4 row_mask:0xf bank_mask:0xf
	v_mul_f32_dpp v34, v34, v34 row_shr:8 row_mask:0xf bank_mask:0xf
	s_nop 0
	v_mul_f32_dpp v35, v35, v35 row_shr:8 row_mask:0xf bank_mask:0xf
	v_mul_f32_dpp v34, v34, v34 row_bcast:15 row_mask:0xa bank_mask:0xf
	v_max_f32_e32 v82, 0x554ad2e, v34
	v_rcp_f32_e32 v84, v82
	v_mul_f32_dpp v35, v35, v35 row_bcast:15 row_mask:0xa bank_mask:0xf
	v_max_f32_e32 v83, 0x554ad2e, v35
	v_rcp_f32_e32 v85, v83
	v_readlane_b32 s0, v82, 31
	v_readlane_b32 s1, v82, 63
	v_pk_mul_f32 v[84:85], v[26:27], v[84:85]
	v_lshlrev_b32_e32 v26, 16, v28
	v_and_b32_e32 v27, 0xffff0000, v28
	v_mul_f32_e32 v28, 0xbfb8aa3b, v26
	v_exp_f32_e32 v28, v28
	v_mul_f32_e32 v77, 0xbfb8aa3b, v27
	v_exp_f32_e32 v77, v77
	v_mov_b32_e32 v34, s1
	v_add_f32_e32 v28, 1.0, v28
	v_rcp_f32_e32 v86, v28
	v_add_f32_e32 v28, 1.0, v77
	v_rcp_f32_e32 v87, v28
	v_mov_b32_e32 v35, s0
	v_readlane_b32 s0, v83, 31
	v_readlane_b32 s1, v83, 63
	v_pk_mul_f32 v[26:27], v[86:87], v[26:27]
	v_cndmask_b32_e64 v34, v34, v35, s[2:3]
	v_mov_b32_e32 v35, s1
	v_mov_b32_e32 v75, s0
	v_pk_mul_f32 v[82:83], v[26:27], v[82:83]
	v_pk_mul_f32 v[26:27], v[44:45], v[46:47]
	v_cmp_nle_f32_e64 s[0:1], 0, v71
	v_pk_add_f32 v[44:45], v[36:37], 1.0 op_sel_hi:[1,0] neg_lo:[1,0] neg_hi:[1,0]
	v_cndmask_b32_e64 v35, v35, v75, s[2:3]
	v_cndmask_b32_e64 v28, v46, v26, s[0:1]
	v_fma_f32 v28, v44, v28, v36
	v_cndmask_b32_e32 v36, v47, v27, vcc
	v_fmac_f32_e32 v37, v45, v36
	v_cndmask_b32_e32 v27, v27, v47, vcc
	v_cndmask_b32_e64 v26, v26, v46, s[0:1]
	v_mul_f32_dpp v28, v28, v28 row_shr:1 row_mask:0xf bank_mask:0xf
	v_pk_mul_f32 v[26:27], v[44:45], v[26:27]
	v_mul_f32_e32 v75, v84, v34
	v_mov_b32_e32 v36, v37
	s_nop 1
	v_mul_f32_dpp v36, v36, v36 row_shr:1 row_mask:0xf bank_mask:0xf
	v_mul_f32_e32 v77, v85, v35
	v_mul_f32_dpp v28, v28, v28 row_shr:2 row_mask:0xf bank_mask:0xf
	v_mul_f32_dpp v36, v36, v36 row_shr:2 row_mask:0xf bank_mask:0xf
	s_nop 0
	v_mul_f32_dpp v28, v28, v28 row_shr:4 row_mask:0xf bank_mask:0xf
	v_mul_f32_dpp v36, v36, v36 row_shr:4 row_mask:0xf bank_mask:0xf
	s_nop 0
	v_mul_f32_dpp v28, v28, v28 row_shr:8 row_mask:0xf bank_mask:0xf
	v_mul_f32_dpp v36, v36, v36 row_shr:8 row_mask:0xf bank_mask:0xf
	s_nop 0
	v_mul_f32_dpp v28, v28, v28 row_bcast:15 row_mask:0xa bank_mask:0xf
	v_max_f32_e32 v44, 0x554ad2e, v28
	v_rcp_f32_e32 v46, v44
	v_mul_f32_dpp v36, v36, v36 row_bcast:15 row_mask:0xa bank_mask:0xf
	v_max_f32_e32 v45, 0x554ad2e, v36
	v_rcp_f32_e32 v47, v45
	v_readlane_b32 s0, v44, 31
	v_readlane_b32 s1, v44, 63
	v_pk_mul_f32 v[46:47], v[26:27], v[46:47]
	s_nop 0
	v_mov_b32_e32 v28, s1
	v_mov_b32_e32 v36, s0
	v_readlane_b32 s0, v45, 31
	v_readlane_b32 s1, v45, 63
	v_cndmask_b32_e64 v36, v28, v36, s[2:3]
	v_mov_b32_e32 v37, s0
	v_mov_b32_e32 v28, s1
	v_lshlrev_b32_e32 v26, 16, v29
	v_and_b32_e32 v27, 0xffff0000, v29
	v_cndmask_b32_e64 v37, v28, v37, s[2:3]
	v_mul_f32_e32 v28, 0xbfb8aa3b, v26
	v_mul_f32_e32 v29, 0xbfb8aa3b, v27
	v_exp_f32_e32 v28, v28
	v_exp_f32_e32 v29, v29
	v_mul_f32_e32 v71, v46, v36
	v_mul_f32_e32 v73, v47, v37
	v_add_f32_e32 v28, 1.0, v28
	v_add_f32_e32 v29, 1.0, v29
	v_rcp_f32_e32 v28, v28
	v_rcp_f32_e32 v29, v29
	s_nop 0
	v_pk_mul_f32 v[26:27], v[28:29], v[26:27]
	v_pk_mul_f32 v[44:45], v[26:27], v[44:45]
	v_cvt_pk_bf16_f32 v26, v48, v49
	v_cvt_pk_bf16_f32 v29, v44, v45
	v_cvt_pk_bf16_f32 v44, v84, v85
	v_cvt_pk_bf16_f32 v45, v46, v47
	v_cvt_pk_bf16_f32 v27, v80, v81
	v_cvt_pk_bf16_f32 v28, v82, v83
	v_xor_b32_e32 v46, v53, v65
	v_lshl_add_u32 v46, v46, 4, v148
	v_mfma_f32_32x32x16_bf16 v[2:17], v[42:45], v[26:29], v[2:17]
	ds_write_b128 v46, v[26:29] offset:20480
	v_cvt_pk_bf16_f32 v46, v79, v90
	ds_write_b16 v56, v46
	ds_write_b16_d16_hi v56, v46 offset:64
	v_cvt_pk_bf16_f32 v46, v91, v92
	ds_write_b16 v56, v46 offset:128
	ds_write_b16_d16_hi v56, v46 offset:192
	v_cvt_pk_bf16_f32 v46, v75, v77
	ds_write_b16 v56, v46 offset:256
	ds_write_b16_d16_hi v56, v46 offset:320
	v_cvt_pk_bf16_f32 v46, v71, v73
	ds_write_b16 v56, v46 offset:384
	ds_write_b16_d16_hi v56, v46 offset:448
	s_and_saveexec_b64 s[0:1], s[4:5]
	s_cbranch_execz .LBB0_593
	v_add_u32_e32 v26, s17, v183
	ds_write_b128 v26, v[30:33]
	ds_write_b128 v26, v[34:37] offset:16
	s_branch .LBB0_593
